# batched loads: fused-LN residual, dif-attn subln epilogue, retention rms loop (16 loads per row up front, stores deferred)
# speedup vs baseline: 1.0072x; 1.0036x over previous
; __device__ __forceinline__ u32x4 pk8(f32x4 a, f32x4 b) { const u32x2 x = pk4(a), y = pk4(b); return (u32x4){x.x, x.y, y.x, y.y}; }
; #define UNPK(w) (f32x4){__uint_as_float((w).x << 16), __uint_as_float((w).x & 0xffff0000u), __uint_as_float((w).y << 16), __uint_as_float((w).y & 0xffff0000u)}
; #define UNPK(w) (f32x4){__uint_as_float((w).x << 16), __uint_as_float((w).x & 0xffff0000u), __uint_as_float((w).y << 16), __uint_as_float((w).y & 0xffff0000u)}
; __global__ void __launch_bounds__(NTHR, 2) fwd(Args args) {
;     ...
;                 for (int row = gw; row < R; row += NGW) {
; #pragma unroll
;                     for (int hh = 0; hh < 8; ++hh) { const size_t o = (size_t)row * 4096 + hh * 512 + lane * 8; const u32x4 ow = __builtin_nontemporal_load((const u32x4*)(O2 + o)), gw4 = __builtin_nontemporal_load((const u32x4*)(SG + o));
;                         const f32x4 v0 = UNPK(((u32x2){ow.x, ow.y})), v1 = UNPK(((u32x2){ow.z, ow.w}));
;                         const float ss = wave_sum((v0[0] * v0[0] + v0[1] * v0[1]) + (v0[2] * v0[2] + v0[3] * v0[3]) + (v1[0] * v1[0] + v1[1] * v1[1]) + (v1[2] * v1[2] + v1[3] * v1[3]), lane);
;                         const float rs = 1.f / sqrtf(ss * (1.f / 512.f) + LN_EPS);
;                         const f32x4 ga = UNPK(((u32x2){gw4.x, gw4.y})), gb2 = UNPK(((u32x2){gw4.z, gw4.w}));
;                         *(u32x4*)(RO + o) = pk8(v0 * rs * ga, v1 * rs * gb2); }
.LBB0_769:
	s_mov_b64 s[98:99], 0x1d400000
	v_lshl_add_u64 v[28:29], v[6:7], 0, s[98:99]
	s_mov_b32 s98, 0xf9400000
	s_mov_b32 s99, -1
	v_lshl_add_u64 v[30:31], v[6:7], 0, s[98:99]
	s_mov_b64 s[98:99], 0x1000
	v_lshl_add_u64 v[160:161], v[28:29], 0, s[98:99]
	v_lshl_add_u64 v[162:163], v[30:31], 0, s[98:99]
	v_lshl_add_u64 v[164:165], v[6:7], 0, s[98:99]
	global_load_dwordx4 v[32:35], v[28:29], off nt
	global_load_dwordx4 v[36:39], v[30:31], off nt
	global_load_dwordx4 v[40:43], v[28:29], off offset:1024 nt
	global_load_dwordx4 v[44:47], v[30:31], off offset:1024 nt
	global_load_dwordx4 v[48:51], v[28:29], off offset:2048 nt
	global_load_dwordx4 v[52:55], v[30:31], off offset:2048 nt
	global_load_dwordx4 v[56:59], v[28:29], off offset:3072 nt
	global_load_dwordx4 v[60:63], v[30:31], off offset:3072 nt
	global_load_dwordx4 v[64:67], v[160:161], off nt
	global_load_dwordx4 v[68:71], v[162:163], off nt
	global_load_dwordx4 v[72:75], v[160:161], off offset:1024 nt
	global_load_dwordx4 v[76:79], v[162:163], off offset:1024 nt
	global_load_dwordx4 v[80:83], v[160:161], off offset:2048 nt
	global_load_dwordx4 v[84:87], v[162:163], off offset:2048 nt
	global_load_dwordx4 v[88:91], v[160:161], off offset:3072 nt
	global_load_dwordx4 v[92:95], v[162:163], off offset:3072 nt
	s_waitcnt vmcnt(14)
	v_lshlrev_b32_e32 v2, 16, v32
	v_and_b32_e32 v3, 0xffff0000, v32
	v_lshlrev_b32_e32 v32, 16, v33
	v_and_b32_e32 v33, 0xffff0000, v33
	v_mul_f32_e32 v0, v3, v3
	v_mul_f32_e32 v22, v33, v33
	v_fmac_f32_e32 v0, v2, v2
	v_fmac_f32_e32 v22, v32, v32
	v_add_f32_e32 v0, v0, v22
	v_lshlrev_b32_e32 v23, 16, v35
	v_lshlrev_b32_e32 v22, 16, v34
	v_and_b32_e32 v35, 0xffff0000, v35
	v_and_b32_e32 v34, 0xffff0000, v34
	v_pk_mul_f32 v[24:25], v[34:35], v[34:35]
	s_nop 0
	v_pk_fma_f32 v[24:25], v[22:23], v[22:23], v[24:25]
	s_nop 0
	v_add_f32_e32 v0, v24, v0
	v_add_f32_e32 v0, v25, v0
	ds_bpermute_b32 v24, v12, v0
	s_waitcnt lgkmcnt(0)
	v_add_f32_e32 v0, v0, v24
	ds_bpermute_b32 v24, v13, v0
	s_waitcnt lgkmcnt(0)
	v_add_f32_e32 v0, v0, v24
	ds_bpermute_b32 v24, v14, v0
	s_waitcnt lgkmcnt(0)
	v_add_f32_e32 v0, v0, v24
	ds_bpermute_b32 v24, v15, v0
	s_waitcnt lgkmcnt(0)
	v_add_f32_e32 v0, v0, v24
	ds_bpermute_b32 v24, v16, v0
	s_waitcnt lgkmcnt(0)
	v_add_f32_e32 v0, v0, v24
	ds_bpermute_b32 v24, v17, v0
	s_waitcnt lgkmcnt(0)
	v_add_f32_e32 v0, v0, v24
	v_fmamk_f32 v0, v0, 0x3b000000, v244
	v_cmp_gt_f32_e32 vcc, s83, v0
	v_mul_f32_e32 v24, 0x4f800000, v0
	s_nop 0
	v_cndmask_b32_e32 v0, v0, v24, vcc
	v_sqrt_f32_e32 v24, v0
	s_nop 0
	v_add_u32_e32 v25, -1, v24
	v_fma_f32 v26, -v25, v24, v0
	v_cmp_ge_f32_e64 s[2:3], 0, v26
	v_add_u32_e32 v26, 1, v24
	s_nop 0
	v_cndmask_b32_e64 v25, v24, v25, s[2:3]
	v_fma_f32 v24, -v26, v24, v0
	v_cmp_lt_f32_e64 s[2:3], 0, v24
	s_nop 1
	v_cndmask_b32_e64 v24, v25, v26, s[2:3]
	v_mul_f32_e32 v25, 0x37800000, v24
	v_cndmask_b32_e32 v24, v24, v25, vcc
	v_cmp_class_f32_e32 vcc, v0, v245
	s_nop 1
	v_cndmask_b32_e32 v0, v24, v0, vcc
	v_div_scale_f32 v24, s[2:3], v0, v0, 1.0
	v_rcp_f32_e32 v25, v24
	s_nop 0
	v_fma_f32 v26, -v24, v25, 1.0
	v_fmac_f32_e32 v25, v26, v25
	v_div_scale_f32 v26, vcc, 1.0, v0, 1.0
	v_mul_f32_e32 v27, v26, v25
	v_fma_f32 v28, -v24, v27, v26
	v_fmac_f32_e32 v27, v28, v25
	v_fma_f32 v24, -v24, v27, v26
	v_div_fmas_f32 v24, v24, v25, v27
	v_div_fixup_f32 v0, v24, v0, 1.0
	v_lshlrev_b32_e32 v24, 16, v36
	v_and_b32_e32 v25, 0xffff0000, v36
	v_lshlrev_b32_e32 v36, 16, v37
	v_and_b32_e32 v37, 0xffff0000, v37
	v_pk_mul_f32 v[32:33], v[32:33], v[0:1] op_sel_hi:[1,0]
	v_lshlrev_b32_e32 v26, 16, v38
	v_pk_mul_f32 v[36:37], v[32:33], v[36:37]
	v_mov_b32_e32 v32, v22
	v_mov_b32_e32 v33, v34
	v_mov_b32_e32 v34, v23
	v_and_b32_e32 v27, 0xffff0000, v38
	v_lshlrev_b32_e32 v38, 16, v39
	v_and_b32_e32 v39, 0xffff0000, v39
	v_pk_mul_f32 v[32:33], v[0:1], v[32:33] op_sel_hi:[0,1]
	v_pk_mul_f32 v[34:35], v[0:1], v[34:35] op_sel_hi:[0,1]
	v_pk_mul_f32 v[2:3], v[2:3], v[0:1] op_sel_hi:[1,0]
	v_pk_mul_f32 v[38:39], v[34:35], v[38:39]
	v_pk_mul_f32 v[34:35], v[32:33], v[26:27]
	v_pk_mul_f32 v[2:3], v[2:3], v[24:25]
	s_nop 0
	v_cvt_pk_bf16_f32 v32, v2, v3
	v_cvt_pk_bf16_f32 v33, v36, v37
	v_cvt_pk_bf16_f32 v34, v34, v35
	v_cvt_pk_bf16_f32 v35, v38, v39
	s_waitcnt vmcnt(12)
	v_lshlrev_b32_e32 v2, 16, v40
	v_and_b32_e32 v3, 0xffff0000, v40
	v_lshlrev_b32_e32 v40, 16, v41
	v_and_b32_e32 v41, 0xffff0000, v41
	v_mul_f32_e32 v0, v3, v3
	v_mul_f32_e32 v22, v41, v41
	v_fmac_f32_e32 v0, v2, v2
	v_fmac_f32_e32 v22, v40, v40
	v_add_f32_e32 v0, v0, v22
	v_lshlrev_b32_e32 v23, 16, v43
	v_lshlrev_b32_e32 v22, 16, v42
	v_and_b32_e32 v43, 0xffff0000, v43
	v_and_b32_e32 v42, 0xffff0000, v42
	v_pk_mul_f32 v[24:25], v[42:43], v[42:43]
	s_nop 0
	v_pk_fma_f32 v[24:25], v[22:23], v[22:23], v[24:25]
	s_nop 0
	v_add_f32_e32 v0, v24, v0
	v_add_f32_e32 v0, v25, v0
	ds_bpermute_b32 v24, v12, v0
	s_waitcnt lgkmcnt(0)
	v_add_f32_e32 v0, v0, v24
	ds_bpermute_b32 v24, v13, v0
	s_waitcnt lgkmcnt(0)
	v_add_f32_e32 v0, v0, v24
	ds_bpermute_b32 v24, v14, v0
	s_waitcnt lgkmcnt(0)
	v_add_f32_e32 v0, v0, v24
	ds_bpermute_b32 v24, v15, v0
	s_waitcnt lgkmcnt(0)
	v_add_f32_e32 v0, v0, v24
	ds_bpermute_b32 v24, v16, v0
	s_waitcnt lgkmcnt(0)
	v_add_f32_e32 v0, v0, v24
	ds_bpermute_b32 v24, v17, v0
	s_waitcnt lgkmcnt(0)
; __device__ __forceinline__ u32x4 pk8(f32x4 a, f32x4 b) { const u32x2 x = pk4(a), y = pk4(b); return (u32x4){x.x, x.y, y.x, y.y}; }
; #define UNPK(w) (f32x4){__uint_as_float((w).x << 16), __uint_as_float((w).x & 0xffff0000u), __uint_as_float((w).y << 16), __uint_as_float((w).y & 0xffff0000u)}
; #define UNPK(w) (f32x4){__uint_as_float((w).x << 16), __uint_as_float((w).x & 0xffff0000u), __uint_as_float((w).y << 16), __uint_as_float((w).y & 0xffff0000u)}
; __global__ void __launch_bounds__(NTHR, 2) fwd(Args args) {
;     ...
;                     for (int hh = 0; hh < 8; ++hh) { const size_t o = (size_t)row * 4096 + hh * 512 + lane * 8; const u32x4 ow = __builtin_nontemporal_load((const u32x4*)(O2 + o)), gw4 = __builtin_nontemporal_load((const u32x4*)(SG + o));
;                         const f32x4 v0 = UNPK(((u32x2){ow.x, ow.y})), v1 = UNPK(((u32x2){ow.z, ow.w}));
;                         const float ss = wave_sum((v0[0] * v0[0] + v0[1] * v0[1]) + (v0[2] * v0[2] + v0[3] * v0[3]) + (v1[0] * v1[0] + v1[1] * v1[1]) + (v1[2] * v1[2] + v1[3] * v1[3]), lane);
;                         const float rs = 1.f / sqrtf(ss * (1.f / 512.f) + LN_EPS);
;                         const f32x4 ga = UNPK(((u32x2){gw4.x, gw4.y})), gb2 = UNPK(((u32x2){gw4.z, gw4.w}));
;                         *(u32x4*)(RO + o) = pk8(v0 * rs * ga, v1 * rs * gb2); }
	v_add_f32_e32 v0, v0, v24
	v_fmamk_f32 v0, v0, 0x3b000000, v244
	v_cmp_gt_f32_e32 vcc, s83, v0
	v_mul_f32_e32 v24, 0x4f800000, v0
	s_nop 0
	v_cndmask_b32_e32 v0, v0, v24, vcc
	v_sqrt_f32_e32 v24, v0
	s_nop 0
	v_add_u32_e32 v25, -1, v24
	v_fma_f32 v26, -v25, v24, v0
	v_cmp_ge_f32_e64 s[2:3], 0, v26
	v_add_u32_e32 v26, 1, v24
	s_nop 0
	v_cndmask_b32_e64 v25, v24, v25, s[2:3]
	v_fma_f32 v24, -v26, v24, v0
	v_cmp_lt_f32_e64 s[2:3], 0, v24
	s_nop 1
	v_cndmask_b32_e64 v24, v25, v26, s[2:3]
	v_mul_f32_e32 v25, 0x37800000, v24
	v_cndmask_b32_e32 v24, v24, v25, vcc
	v_cmp_class_f32_e32 vcc, v0, v245
	s_nop 1
	v_cndmask_b32_e32 v0, v24, v0, vcc
	v_div_scale_f32 v24, s[2:3], v0, v0, 1.0
	v_rcp_f32_e32 v25, v24
	s_nop 0
	v_fma_f32 v26, -v24, v25, 1.0
	v_fmac_f32_e32 v25, v26, v25
	v_div_scale_f32 v26, vcc, 1.0, v0, 1.0
	v_mul_f32_e32 v27, v26, v25
	v_fma_f32 v28, -v24, v27, v26
	v_fmac_f32_e32 v27, v28, v25
	v_fma_f32 v24, -v24, v27, v26
	v_div_fmas_f32 v24, v24, v25, v27
	v_div_fixup_f32 v0, v24, v0, 1.0
	v_lshlrev_b32_e32 v24, 16, v44
	v_and_b32_e32 v25, 0xffff0000, v44
	v_lshlrev_b32_e32 v44, 16, v45
	v_and_b32_e32 v45, 0xffff0000, v45
	v_pk_mul_f32 v[40:41], v[40:41], v[0:1] op_sel_hi:[1,0]
	v_lshlrev_b32_e32 v26, 16, v46
	v_pk_mul_f32 v[44:45], v[40:41], v[44:45]
	v_mov_b32_e32 v40, v22
	v_mov_b32_e32 v41, v42
	v_mov_b32_e32 v42, v23
	v_and_b32_e32 v27, 0xffff0000, v46
	v_lshlrev_b32_e32 v46, 16, v47
	v_and_b32_e32 v47, 0xffff0000, v47
	v_pk_mul_f32 v[40:41], v[0:1], v[40:41] op_sel_hi:[0,1]
	v_pk_mul_f32 v[42:43], v[0:1], v[42:43] op_sel_hi:[0,1]
	v_pk_mul_f32 v[2:3], v[2:3], v[0:1] op_sel_hi:[1,0]
	v_pk_mul_f32 v[46:47], v[42:43], v[46:47]
	v_pk_mul_f32 v[42:43], v[40:41], v[26:27]
	v_pk_mul_f32 v[2:3], v[2:3], v[24:25]
	s_nop 0
	v_cvt_pk_bf16_f32 v40, v2, v3
	v_cvt_pk_bf16_f32 v41, v44, v45
	v_cvt_pk_bf16_f32 v42, v42, v43
	v_cvt_pk_bf16_f32 v43, v46, v47
	s_waitcnt vmcnt(10)
	v_lshlrev_b32_e32 v2, 16, v48
	v_and_b32_e32 v3, 0xffff0000, v48
	v_lshlrev_b32_e32 v48, 16, v49
	v_and_b32_e32 v49, 0xffff0000, v49
	v_mul_f32_e32 v0, v3, v3
	v_mul_f32_e32 v22, v49, v49
	v_fmac_f32_e32 v0, v2, v2
	v_fmac_f32_e32 v22, v48, v48
	v_add_f32_e32 v0, v0, v22
	v_lshlrev_b32_e32 v23, 16, v51
	v_lshlrev_b32_e32 v22, 16, v50
	v_and_b32_e32 v51, 0xffff0000, v51
	v_and_b32_e32 v50, 0xffff0000, v50
	v_pk_mul_f32 v[24:25], v[50:51], v[50:51]
	s_nop 0
	v_pk_fma_f32 v[24:25], v[22:23], v[22:23], v[24:25]
	s_nop 0
	v_add_f32_e32 v0, v24, v0
	v_add_f32_e32 v0, v25, v0
	ds_bpermute_b32 v24, v12, v0
	s_waitcnt lgkmcnt(0)
	v_add_f32_e32 v0, v0, v24
	ds_bpermute_b32 v24, v13, v0
	s_waitcnt lgkmcnt(0)
	v_add_f32_e32 v0, v0, v24
	ds_bpermute_b32 v24, v14, v0
	s_waitcnt lgkmcnt(0)
	v_add_f32_e32 v0, v0, v24
	ds_bpermute_b32 v24, v15, v0
	s_waitcnt lgkmcnt(0)
	v_add_f32_e32 v0, v0, v24
	ds_bpermute_b32 v24, v16, v0
	s_waitcnt lgkmcnt(0)
	v_add_f32_e32 v0, v0, v24
	ds_bpermute_b32 v24, v17, v0
	s_waitcnt lgkmcnt(0)
	v_add_f32_e32 v0, v0, v24
	v_fmamk_f32 v0, v0, 0x3b000000, v244
	v_cmp_gt_f32_e32 vcc, s83, v0
	v_mul_f32_e32 v24, 0x4f800000, v0
	s_nop 0
	v_cndmask_b32_e32 v0, v0, v24, vcc
	v_sqrt_f32_e32 v24, v0
	s_nop 0
	v_add_u32_e32 v25, -1, v24
	v_fma_f32 v26, -v25, v24, v0
	v_cmp_ge_f32_e64 s[2:3], 0, v26
	v_add_u32_e32 v26, 1, v24
	s_nop 0
	v_cndmask_b32_e64 v25, v24, v25, s[2:3]
	v_fma_f32 v24, -v26, v24, v0
	v_cmp_lt_f32_e64 s[2:3], 0, v24
	s_nop 1
	v_cndmask_b32_e64 v24, v25, v26, s[2:3]
	v_mul_f32_e32 v25, 0x37800000, v24
	v_cndmask_b32_e32 v24, v24, v25, vcc
	v_cmp_class_f32_e32 vcc, v0, v245
	s_nop 1
	v_cndmask_b32_e32 v0, v24, v0, vcc
	v_div_scale_f32 v24, s[2:3], v0, v0, 1.0
	v_rcp_f32_e32 v25, v24
	s_nop 0
	v_fma_f32 v26, -v24, v25, 1.0
	v_fmac_f32_e32 v25, v26, v25
	v_div_scale_f32 v26, vcc, 1.0, v0, 1.0
	v_mul_f32_e32 v27, v26, v25
	v_fma_f32 v28, -v24, v27, v26
	v_fmac_f32_e32 v27, v28, v25
	v_fma_f32 v24, -v24, v27, v26
	v_div_fmas_f32 v24, v24, v25, v27
	v_div_fixup_f32 v0, v24, v0, 1.0
	v_lshlrev_b32_e32 v24, 16, v52
	v_and_b32_e32 v25, 0xffff0000, v52
	v_lshlrev_b32_e32 v52, 16, v53
	v_and_b32_e32 v53, 0xffff0000, v53
	v_pk_mul_f32 v[48:49], v[48:49], v[0:1] op_sel_hi:[1,0]
	v_lshlrev_b32_e32 v26, 16, v54
	v_pk_mul_f32 v[52:53], v[48:49], v[52:53]
	v_mov_b32_e32 v48, v22
	v_mov_b32_e32 v49, v50
	v_mov_b32_e32 v50, v23
	v_and_b32_e32 v27, 0xffff0000, v54
	v_lshlrev_b32_e32 v54, 16, v55
	v_and_b32_e32 v55, 0xffff0000, v55
	v_pk_mul_f32 v[48:49], v[0:1], v[48:49] op_sel_hi:[0,1]
	v_pk_mul_f32 v[50:51], v[0:1], v[50:51] op_sel_hi:[0,1]
	v_pk_mul_f32 v[2:3], v[2:3], v[0:1] op_sel_hi:[1,0]
	v_pk_mul_f32 v[54:55], v[50:51], v[54:55]
	v_pk_mul_f32 v[50:51], v[48:49], v[26:27]
	v_pk_mul_f32 v[2:3], v[2:3], v[24:25]
	s_nop 0
	v_cvt_pk_bf16_f32 v48, v2, v3
	v_cvt_pk_bf16_f32 v49, v52, v53
	v_cvt_pk_bf16_f32 v50, v50, v51
	v_cvt_pk_bf16_f32 v51, v54, v55
	s_waitcnt vmcnt(8)
	v_lshlrev_b32_e32 v2, 16, v56
	v_and_b32_e32 v3, 0xffff0000, v56
	v_lshlrev_b32_e32 v56, 16, v57
	v_and_b32_e32 v57, 0xffff0000, v57
	v_mul_f32_e32 v0, v3, v3
	v_mul_f32_e32 v22, v57, v57
	v_fmac_f32_e32 v0, v2, v2
	v_fmac_f32_e32 v22, v56, v56
	v_add_f32_e32 v0, v0, v22
	v_lshlrev_b32_e32 v23, 16, v59
	v_lshlrev_b32_e32 v22, 16, v58
	v_and_b32_e32 v59, 0xffff0000, v59
	v_and_b32_e32 v58, 0xffff0000, v58
	v_pk_mul_f32 v[24:25], v[58:59], v[58:59]
	s_nop 0
	v_pk_fma_f32 v[24:25], v[22:23], v[22:23], v[24:25]
	s_nop 0
	v_add_f32_e32 v0, v24, v0
	v_add_f32_e32 v0, v25, v0
	ds_bpermute_b32 v24, v12, v0
	s_waitcnt lgkmcnt(0)
	v_add_f32_e32 v0, v0, v24
	ds_bpermute_b32 v24, v13, v0
	s_waitcnt lgkmcnt(0)
	v_add_f32_e32 v0, v0, v24
	ds_bpermute_b32 v24, v14, v0
	s_waitcnt lgkmcnt(0)
; __device__ __forceinline__ u32x4 pk8(f32x4 a, f32x4 b) { const u32x2 x = pk4(a), y = pk4(b); return (u32x4){x.x, x.y, y.x, y.y}; }
; #define UNPK(w) (f32x4){__uint_as_float((w).x << 16), __uint_as_float((w).x & 0xffff0000u), __uint_as_float((w).y << 16), __uint_as_float((w).y & 0xffff0000u)}
; #define UNPK(w) (f32x4){__uint_as_float((w).x << 16), __uint_as_float((w).x & 0xffff0000u), __uint_as_float((w).y << 16), __uint_as_float((w).y & 0xffff0000u)}
; __global__ void __launch_bounds__(NTHR, 2) fwd(Args args) {
;     ...
;                     for (int hh = 0; hh < 8; ++hh) { const size_t o = (size_t)row * 4096 + hh * 512 + lane * 8; const u32x4 ow = __builtin_nontemporal_load((const u32x4*)(O2 + o)), gw4 = __builtin_nontemporal_load((const u32x4*)(SG + o));
;                         const f32x4 v0 = UNPK(((u32x2){ow.x, ow.y})), v1 = UNPK(((u32x2){ow.z, ow.w}));
;                         const float ss = wave_sum((v0[0] * v0[0] + v0[1] * v0[1]) + (v0[2] * v0[2] + v0[3] * v0[3]) + (v1[0] * v1[0] + v1[1] * v1[1]) + (v1[2] * v1[2] + v1[3] * v1[3]), lane);
;                         const float rs = 1.f / sqrtf(ss * (1.f / 512.f) + LN_EPS);
;                         const f32x4 ga = UNPK(((u32x2){gw4.x, gw4.y})), gb2 = UNPK(((u32x2){gw4.z, gw4.w}));
;                         *(u32x4*)(RO + o) = pk8(v0 * rs * ga, v1 * rs * gb2); }
	v_add_f32_e32 v0, v0, v24
	ds_bpermute_b32 v24, v15, v0
	s_waitcnt lgkmcnt(0)
	v_add_f32_e32 v0, v0, v24
	ds_bpermute_b32 v24, v16, v0
	s_waitcnt lgkmcnt(0)
	v_add_f32_e32 v0, v0, v24
	ds_bpermute_b32 v24, v17, v0
	s_waitcnt lgkmcnt(0)
	v_add_f32_e32 v0, v0, v24
	v_fmamk_f32 v0, v0, 0x3b000000, v244
	v_cmp_gt_f32_e32 vcc, s83, v0
	v_mul_f32_e32 v24, 0x4f800000, v0
	s_nop 0
	v_cndmask_b32_e32 v0, v0, v24, vcc
	v_sqrt_f32_e32 v24, v0
	s_nop 0
	v_add_u32_e32 v25, -1, v24
	v_fma_f32 v26, -v25, v24, v0
	v_cmp_ge_f32_e64 s[2:3], 0, v26
	v_add_u32_e32 v26, 1, v24
	s_nop 0
	v_cndmask_b32_e64 v25, v24, v25, s[2:3]
	v_fma_f32 v24, -v26, v24, v0
	v_cmp_lt_f32_e64 s[2:3], 0, v24
	s_nop 1
	v_cndmask_b32_e64 v24, v25, v26, s[2:3]
	v_mul_f32_e32 v25, 0x37800000, v24
	v_cndmask_b32_e32 v24, v24, v25, vcc
	v_cmp_class_f32_e32 vcc, v0, v245
	s_nop 1
	v_cndmask_b32_e32 v0, v24, v0, vcc
	v_div_scale_f32 v24, s[2:3], v0, v0, 1.0
	v_rcp_f32_e32 v25, v24
	s_nop 0
	v_fma_f32 v26, -v24, v25, 1.0
	v_fmac_f32_e32 v25, v26, v25
	v_div_scale_f32 v26, vcc, 1.0, v0, 1.0
	v_mul_f32_e32 v27, v26, v25
	v_fma_f32 v28, -v24, v27, v26
	v_fmac_f32_e32 v27, v28, v25
	v_fma_f32 v24, -v24, v27, v26
	v_div_fmas_f32 v24, v24, v25, v27
	v_div_fixup_f32 v0, v24, v0, 1.0
	v_lshlrev_b32_e32 v24, 16, v60
	v_and_b32_e32 v25, 0xffff0000, v60
	v_lshlrev_b32_e32 v60, 16, v61
	v_and_b32_e32 v61, 0xffff0000, v61
	v_pk_mul_f32 v[56:57], v[56:57], v[0:1] op_sel_hi:[1,0]
	v_lshlrev_b32_e32 v26, 16, v62
	v_pk_mul_f32 v[60:61], v[56:57], v[60:61]
	v_mov_b32_e32 v56, v22
	v_mov_b32_e32 v57, v58
	v_mov_b32_e32 v58, v23
	v_and_b32_e32 v27, 0xffff0000, v62
	v_lshlrev_b32_e32 v62, 16, v63
	v_and_b32_e32 v63, 0xffff0000, v63
	v_pk_mul_f32 v[56:57], v[0:1], v[56:57] op_sel_hi:[0,1]
	v_pk_mul_f32 v[58:59], v[0:1], v[58:59] op_sel_hi:[0,1]
	v_pk_mul_f32 v[2:3], v[2:3], v[0:1] op_sel_hi:[1,0]
	v_pk_mul_f32 v[62:63], v[58:59], v[62:63]
	v_pk_mul_f32 v[58:59], v[56:57], v[26:27]
	v_pk_mul_f32 v[2:3], v[2:3], v[24:25]
	s_nop 0
	v_cvt_pk_bf16_f32 v56, v2, v3
	v_cvt_pk_bf16_f32 v57, v60, v61
	v_cvt_pk_bf16_f32 v58, v58, v59
	v_cvt_pk_bf16_f32 v59, v62, v63
	s_waitcnt vmcnt(6)
	v_lshlrev_b32_e32 v2, 16, v64
	v_and_b32_e32 v3, 0xffff0000, v64
	v_lshlrev_b32_e32 v64, 16, v65
	v_and_b32_e32 v65, 0xffff0000, v65
	v_mul_f32_e32 v0, v3, v3
	v_mul_f32_e32 v22, v65, v65
	v_fmac_f32_e32 v0, v2, v2
	v_fmac_f32_e32 v22, v64, v64
	v_add_f32_e32 v0, v0, v22
	v_lshlrev_b32_e32 v23, 16, v67
	v_lshlrev_b32_e32 v22, 16, v66
	v_and_b32_e32 v67, 0xffff0000, v67
	v_and_b32_e32 v66, 0xffff0000, v66
	v_pk_mul_f32 v[24:25], v[66:67], v[66:67]
	s_nop 0
	v_pk_fma_f32 v[24:25], v[22:23], v[22:23], v[24:25]
	s_nop 0
	v_add_f32_e32 v0, v24, v0
	v_add_f32_e32 v0, v25, v0
	ds_bpermute_b32 v24, v12, v0
	s_waitcnt lgkmcnt(0)
	v_add_f32_e32 v0, v0, v24
	ds_bpermute_b32 v24, v13, v0
	s_waitcnt lgkmcnt(0)
	v_add_f32_e32 v0, v0, v24
	ds_bpermute_b32 v24, v14, v0
	s_waitcnt lgkmcnt(0)
	v_add_f32_e32 v0, v0, v24
	ds_bpermute_b32 v24, v15, v0
	s_waitcnt lgkmcnt(0)
	v_add_f32_e32 v0, v0, v24
	ds_bpermute_b32 v24, v16, v0
	s_waitcnt lgkmcnt(0)
	v_add_f32_e32 v0, v0, v24
	ds_bpermute_b32 v24, v17, v0
	s_waitcnt lgkmcnt(0)
	v_add_f32_e32 v0, v0, v24
	v_fmamk_f32 v0, v0, 0x3b000000, v244
	v_cmp_gt_f32_e32 vcc, s83, v0
	v_mul_f32_e32 v24, 0x4f800000, v0
	s_nop 0
	v_cndmask_b32_e32 v0, v0, v24, vcc
	v_sqrt_f32_e32 v24, v0
	s_nop 0
	v_add_u32_e32 v25, -1, v24
	v_fma_f32 v26, -v25, v24, v0
	v_cmp_ge_f32_e64 s[2:3], 0, v26
	v_add_u32_e32 v26, 1, v24
	s_nop 0
	v_cndmask_b32_e64 v25, v24, v25, s[2:3]
	v_fma_f32 v24, -v26, v24, v0
	v_cmp_lt_f32_e64 s[2:3], 0, v24
	s_nop 1
	v_cndmask_b32_e64 v24, v25, v26, s[2:3]
	v_mul_f32_e32 v25, 0x37800000, v24
	v_cndmask_b32_e32 v24, v24, v25, vcc
	v_cmp_class_f32_e32 vcc, v0, v245
	s_nop 1
	v_cndmask_b32_e32 v0, v24, v0, vcc
	v_div_scale_f32 v24, s[2:3], v0, v0, 1.0
	v_rcp_f32_e32 v25, v24
	s_nop 0
	v_fma_f32 v26, -v24, v25, 1.0
	v_fmac_f32_e32 v25, v26, v25
	v_div_scale_f32 v26, vcc, 1.0, v0, 1.0
	v_mul_f32_e32 v27, v26, v25
	v_fma_f32 v28, -v24, v27, v26
	v_fmac_f32_e32 v27, v28, v25
	v_fma_f32 v24, -v24, v27, v26
	v_div_fmas_f32 v24, v24, v25, v27
	v_div_fixup_f32 v0, v24, v0, 1.0
	v_lshlrev_b32_e32 v24, 16, v68
	v_and_b32_e32 v25, 0xffff0000, v68
	v_lshlrev_b32_e32 v68, 16, v69
	v_and_b32_e32 v69, 0xffff0000, v69
	v_pk_mul_f32 v[64:65], v[64:65], v[0:1] op_sel_hi:[1,0]
	v_lshlrev_b32_e32 v26, 16, v70
	v_pk_mul_f32 v[68:69], v[64:65], v[68:69]
	v_mov_b32_e32 v64, v22
	v_mov_b32_e32 v65, v66
	v_mov_b32_e32 v66, v23
	v_and_b32_e32 v27, 0xffff0000, v70
	v_lshlrev_b32_e32 v70, 16, v71
	v_and_b32_e32 v71, 0xffff0000, v71
	v_pk_mul_f32 v[64:65], v[0:1], v[64:65] op_sel_hi:[0,1]
	v_pk_mul_f32 v[66:67], v[0:1], v[66:67] op_sel_hi:[0,1]
	v_pk_mul_f32 v[2:3], v[2:3], v[0:1] op_sel_hi:[1,0]
	v_pk_mul_f32 v[70:71], v[66:67], v[70:71]
	v_pk_mul_f32 v[66:67], v[64:65], v[26:27]
	v_pk_mul_f32 v[2:3], v[2:3], v[24:25]
	s_nop 0
	v_cvt_pk_bf16_f32 v64, v2, v3
	v_cvt_pk_bf16_f32 v65, v68, v69
	v_cvt_pk_bf16_f32 v66, v66, v67
	v_cvt_pk_bf16_f32 v67, v70, v71
	s_waitcnt vmcnt(4)
	v_lshlrev_b32_e32 v2, 16, v72
	v_and_b32_e32 v3, 0xffff0000, v72
	v_lshlrev_b32_e32 v72, 16, v73
	v_and_b32_e32 v73, 0xffff0000, v73
	v_mul_f32_e32 v0, v3, v3
	v_mul_f32_e32 v22, v73, v73
	v_fmac_f32_e32 v0, v2, v2
	v_fmac_f32_e32 v22, v72, v72
	v_add_f32_e32 v0, v0, v22
	v_lshlrev_b32_e32 v23, 16, v75
	v_lshlrev_b32_e32 v22, 16, v74
	v_and_b32_e32 v75, 0xffff0000, v75
	v_and_b32_e32 v74, 0xffff0000, v74
	v_pk_mul_f32 v[24:25], v[74:75], v[74:75]
	s_nop 0
	v_pk_fma_f32 v[24:25], v[22:23], v[22:23], v[24:25]
	s_nop 0
	v_add_f32_e32 v0, v24, v0
	v_add_f32_e32 v0, v25, v0
	ds_bpermute_b32 v24, v12, v0
	s_waitcnt lgkmcnt(0)
; __device__ __forceinline__ u32x4 pk8(f32x4 a, f32x4 b) { const u32x2 x = pk4(a), y = pk4(b); return (u32x4){x.x, x.y, y.x, y.y}; }
; #define UNPK(w) (f32x4){__uint_as_float((w).x << 16), __uint_as_float((w).x & 0xffff0000u), __uint_as_float((w).y << 16), __uint_as_float((w).y & 0xffff0000u)}
; #define UNPK(w) (f32x4){__uint_as_float((w).x << 16), __uint_as_float((w).x & 0xffff0000u), __uint_as_float((w).y << 16), __uint_as_float((w).y & 0xffff0000u)}
; __global__ void __launch_bounds__(NTHR, 2) fwd(Args args) {
;     ...
;                     for (int hh = 0; hh < 8; ++hh) { const size_t o = (size_t)row * 4096 + hh * 512 + lane * 8; const u32x4 ow = __builtin_nontemporal_load((const u32x4*)(O2 + o)), gw4 = __builtin_nontemporal_load((const u32x4*)(SG + o));
;                         const f32x4 v0 = UNPK(((u32x2){ow.x, ow.y})), v1 = UNPK(((u32x2){ow.z, ow.w}));
;                         const float ss = wave_sum((v0[0] * v0[0] + v0[1] * v0[1]) + (v0[2] * v0[2] + v0[3] * v0[3]) + (v1[0] * v1[0] + v1[1] * v1[1]) + (v1[2] * v1[2] + v1[3] * v1[3]), lane);
;                         const float rs = 1.f / sqrtf(ss * (1.f / 512.f) + LN_EPS);
;                         const f32x4 ga = UNPK(((u32x2){gw4.x, gw4.y})), gb2 = UNPK(((u32x2){gw4.z, gw4.w}));
;                         *(u32x4*)(RO + o) = pk8(v0 * rs * ga, v1 * rs * gb2); }
	v_add_f32_e32 v0, v0, v24
	ds_bpermute_b32 v24, v13, v0
	s_waitcnt lgkmcnt(0)
	v_add_f32_e32 v0, v0, v24
	ds_bpermute_b32 v24, v14, v0
	s_waitcnt lgkmcnt(0)
	v_add_f32_e32 v0, v0, v24
	ds_bpermute_b32 v24, v15, v0
	s_waitcnt lgkmcnt(0)
	v_add_f32_e32 v0, v0, v24
	ds_bpermute_b32 v24, v16, v0
	s_waitcnt lgkmcnt(0)
	v_add_f32_e32 v0, v0, v24
	ds_bpermute_b32 v24, v17, v0
	s_waitcnt lgkmcnt(0)
	v_add_f32_e32 v0, v0, v24
	v_fmamk_f32 v0, v0, 0x3b000000, v244
	v_cmp_gt_f32_e32 vcc, s83, v0
	v_mul_f32_e32 v24, 0x4f800000, v0
	s_nop 0
	v_cndmask_b32_e32 v0, v0, v24, vcc
	v_sqrt_f32_e32 v24, v0
	s_nop 0
	v_add_u32_e32 v25, -1, v24
	v_fma_f32 v26, -v25, v24, v0
	v_cmp_ge_f32_e64 s[2:3], 0, v26
	v_add_u32_e32 v26, 1, v24
	s_nop 0
	v_cndmask_b32_e64 v25, v24, v25, s[2:3]
	v_fma_f32 v24, -v26, v24, v0
	v_cmp_lt_f32_e64 s[2:3], 0, v24
	s_nop 1
	v_cndmask_b32_e64 v24, v25, v26, s[2:3]
	v_mul_f32_e32 v25, 0x37800000, v24
	v_cndmask_b32_e32 v24, v24, v25, vcc
	v_cmp_class_f32_e32 vcc, v0, v245
	s_nop 1
	v_cndmask_b32_e32 v0, v24, v0, vcc
	v_div_scale_f32 v24, s[2:3], v0, v0, 1.0
	v_rcp_f32_e32 v25, v24
	s_nop 0
	v_fma_f32 v26, -v24, v25, 1.0
	v_fmac_f32_e32 v25, v26, v25
	v_div_scale_f32 v26, vcc, 1.0, v0, 1.0
	v_mul_f32_e32 v27, v26, v25
	v_fma_f32 v28, -v24, v27, v26
	v_fmac_f32_e32 v27, v28, v25
	v_fma_f32 v24, -v24, v27, v26
	v_div_fmas_f32 v24, v24, v25, v27
	v_div_fixup_f32 v0, v24, v0, 1.0
	v_lshlrev_b32_e32 v24, 16, v76
	v_and_b32_e32 v25, 0xffff0000, v76
	v_lshlrev_b32_e32 v76, 16, v77
	v_and_b32_e32 v77, 0xffff0000, v77
	v_pk_mul_f32 v[72:73], v[72:73], v[0:1] op_sel_hi:[1,0]
	v_lshlrev_b32_e32 v26, 16, v78
	v_pk_mul_f32 v[76:77], v[72:73], v[76:77]
	v_mov_b32_e32 v72, v22
	v_mov_b32_e32 v73, v74
	v_mov_b32_e32 v74, v23
	v_and_b32_e32 v27, 0xffff0000, v78
	v_lshlrev_b32_e32 v78, 16, v79
	v_and_b32_e32 v79, 0xffff0000, v79
	v_pk_mul_f32 v[72:73], v[0:1], v[72:73] op_sel_hi:[0,1]
	v_pk_mul_f32 v[74:75], v[0:1], v[74:75] op_sel_hi:[0,1]
	v_pk_mul_f32 v[2:3], v[2:3], v[0:1] op_sel_hi:[1,0]
	v_pk_mul_f32 v[78:79], v[74:75], v[78:79]
	v_pk_mul_f32 v[74:75], v[72:73], v[26:27]
	v_pk_mul_f32 v[2:3], v[2:3], v[24:25]
	s_nop 0
	v_cvt_pk_bf16_f32 v72, v2, v3
	v_cvt_pk_bf16_f32 v73, v76, v77
	v_cvt_pk_bf16_f32 v74, v74, v75
	v_cvt_pk_bf16_f32 v75, v78, v79
	s_waitcnt vmcnt(2)
	v_lshlrev_b32_e32 v2, 16, v80
	v_and_b32_e32 v3, 0xffff0000, v80
	v_lshlrev_b32_e32 v80, 16, v81
	v_and_b32_e32 v81, 0xffff0000, v81
	v_mul_f32_e32 v0, v3, v3
	v_mul_f32_e32 v22, v81, v81
	v_fmac_f32_e32 v0, v2, v2
	v_fmac_f32_e32 v22, v80, v80
	v_add_f32_e32 v0, v0, v22
	v_lshlrev_b32_e32 v23, 16, v83
	v_lshlrev_b32_e32 v22, 16, v82
	v_and_b32_e32 v83, 0xffff0000, v83
	v_and_b32_e32 v82, 0xffff0000, v82
	v_pk_mul_f32 v[24:25], v[82:83], v[82:83]
	s_nop 0
	v_pk_fma_f32 v[24:25], v[22:23], v[22:23], v[24:25]
	s_nop 0
	v_add_f32_e32 v0, v24, v0
	v_add_f32_e32 v0, v25, v0
	ds_bpermute_b32 v24, v12, v0
	s_waitcnt lgkmcnt(0)
	v_add_f32_e32 v0, v0, v24
	ds_bpermute_b32 v24, v13, v0
	s_waitcnt lgkmcnt(0)
	v_add_f32_e32 v0, v0, v24
	ds_bpermute_b32 v24, v14, v0
	s_waitcnt lgkmcnt(0)
	v_add_f32_e32 v0, v0, v24
	ds_bpermute_b32 v24, v15, v0
	s_waitcnt lgkmcnt(0)
	v_add_f32_e32 v0, v0, v24
	ds_bpermute_b32 v24, v16, v0
	s_waitcnt lgkmcnt(0)
	v_add_f32_e32 v0, v0, v24
	ds_bpermute_b32 v24, v17, v0
	s_waitcnt lgkmcnt(0)
	v_add_f32_e32 v0, v0, v24
	v_fmamk_f32 v0, v0, 0x3b000000, v244
	v_cmp_gt_f32_e32 vcc, s83, v0
	v_mul_f32_e32 v24, 0x4f800000, v0
	s_nop 0
	v_cndmask_b32_e32 v0, v0, v24, vcc
	v_sqrt_f32_e32 v24, v0
	s_nop 0
	v_add_u32_e32 v25, -1, v24
	v_fma_f32 v26, -v25, v24, v0
	v_cmp_ge_f32_e64 s[2:3], 0, v26
	v_add_u32_e32 v26, 1, v24
	s_nop 0
	v_cndmask_b32_e64 v25, v24, v25, s[2:3]
	v_fma_f32 v24, -v26, v24, v0
	v_cmp_lt_f32_e64 s[2:3], 0, v24
	s_nop 1
	v_cndmask_b32_e64 v24, v25, v26, s[2:3]
	v_mul_f32_e32 v25, 0x37800000, v24
	v_cndmask_b32_e32 v24, v24, v25, vcc
	v_cmp_class_f32_e32 vcc, v0, v245
	s_nop 1
	v_cndmask_b32_e32 v0, v24, v0, vcc
	v_div_scale_f32 v24, s[2:3], v0, v0, 1.0
	v_rcp_f32_e32 v25, v24
	s_nop 0
	v_fma_f32 v26, -v24, v25, 1.0
	v_fmac_f32_e32 v25, v26, v25
	v_div_scale_f32 v26, vcc, 1.0, v0, 1.0
	v_mul_f32_e32 v27, v26, v25
	v_fma_f32 v28, -v24, v27, v26
	v_fmac_f32_e32 v27, v28, v25
	v_fma_f32 v24, -v24, v27, v26
	v_div_fmas_f32 v24, v24, v25, v27
	v_div_fixup_f32 v0, v24, v0, 1.0
	v_lshlrev_b32_e32 v24, 16, v84
	v_and_b32_e32 v25, 0xffff0000, v84
	v_lshlrev_b32_e32 v84, 16, v85
	v_and_b32_e32 v85, 0xffff0000, v85
	v_pk_mul_f32 v[80:81], v[80:81], v[0:1] op_sel_hi:[1,0]
	v_lshlrev_b32_e32 v26, 16, v86
	v_pk_mul_f32 v[84:85], v[80:81], v[84:85]
	v_mov_b32_e32 v80, v22
	v_mov_b32_e32 v81, v82
	v_mov_b32_e32 v82, v23
	v_and_b32_e32 v27, 0xffff0000, v86
	v_lshlrev_b32_e32 v86, 16, v87
	v_and_b32_e32 v87, 0xffff0000, v87
	v_pk_mul_f32 v[80:81], v[0:1], v[80:81] op_sel_hi:[0,1]
	v_pk_mul_f32 v[82:83], v[0:1], v[82:83] op_sel_hi:[0,1]
	v_pk_mul_f32 v[2:3], v[2:3], v[0:1] op_sel_hi:[1,0]
	v_pk_mul_f32 v[86:87], v[82:83], v[86:87]
	v_pk_mul_f32 v[82:83], v[80:81], v[26:27]
	v_pk_mul_f32 v[2:3], v[2:3], v[24:25]
	s_nop 0
	v_cvt_pk_bf16_f32 v80, v2, v3
	v_cvt_pk_bf16_f32 v81, v84, v85
	v_cvt_pk_bf16_f32 v82, v82, v83
	v_cvt_pk_bf16_f32 v83, v86, v87
	s_waitcnt vmcnt(0)
; __device__ __forceinline__ u32x4 pk8(f32x4 a, f32x4 b) { const u32x2 x = pk4(a), y = pk4(b); return (u32x4){x.x, x.y, y.x, y.y}; }
; #define UNPK(w) (f32x4){__uint_as_float((w).x << 16), __uint_as_float((w).x & 0xffff0000u), __uint_as_float((w).y << 16), __uint_as_float((w).y & 0xffff0000u)}
; #define UNPK(w) (f32x4){__uint_as_float((w).x << 16), __uint_as_float((w).x & 0xffff0000u), __uint_as_float((w).y << 16), __uint_as_float((w).y & 0xffff0000u)}
; __global__ void __launch_bounds__(NTHR, 2) fwd(Args args) {
;     ...
;                     for (int hh = 0; hh < 8; ++hh) { const size_t o = (size_t)row * 4096 + hh * 512 + lane * 8; const u32x4 ow = __builtin_nontemporal_load((const u32x4*)(O2 + o)), gw4 = __builtin_nontemporal_load((const u32x4*)(SG + o));
;                         const f32x4 v0 = UNPK(((u32x2){ow.x, ow.y})), v1 = UNPK(((u32x2){ow.z, ow.w}));
;                         const float ss = wave_sum((v0[0] * v0[0] + v0[1] * v0[1]) + (v0[2] * v0[2] + v0[3] * v0[3]) + (v1[0] * v1[0] + v1[1] * v1[1]) + (v1[2] * v1[2] + v1[3] * v1[3]), lane);
;                         const float rs = 1.f / sqrtf(ss * (1.f / 512.f) + LN_EPS);
;                         const f32x4 ga = UNPK(((u32x2){gw4.x, gw4.y})), gb2 = UNPK(((u32x2){gw4.z, gw4.w}));
;                         *(u32x4*)(RO + o) = pk8(v0 * rs * ga, v1 * rs * gb2); }
	v_lshlrev_b32_e32 v2, 16, v88
	v_and_b32_e32 v3, 0xffff0000, v88
	v_lshlrev_b32_e32 v88, 16, v89
	v_and_b32_e32 v89, 0xffff0000, v89
	v_mul_f32_e32 v0, v3, v3
	v_mul_f32_e32 v22, v89, v89
	v_fmac_f32_e32 v0, v2, v2
	v_fmac_f32_e32 v22, v88, v88
	v_add_f32_e32 v0, v0, v22
	v_lshlrev_b32_e32 v23, 16, v91
	v_lshlrev_b32_e32 v22, 16, v90
	v_and_b32_e32 v91, 0xffff0000, v91
	v_and_b32_e32 v90, 0xffff0000, v90
	v_pk_mul_f32 v[24:25], v[90:91], v[90:91]
	s_nop 0
	v_pk_fma_f32 v[24:25], v[22:23], v[22:23], v[24:25]
	s_nop 0
	v_add_f32_e32 v0, v24, v0
	v_add_f32_e32 v0, v25, v0
	ds_bpermute_b32 v24, v12, v0
	s_waitcnt lgkmcnt(0)
	v_add_f32_e32 v0, v0, v24
	ds_bpermute_b32 v24, v13, v0
	s_waitcnt lgkmcnt(0)
	v_add_f32_e32 v0, v0, v24
	ds_bpermute_b32 v24, v14, v0
	s_waitcnt lgkmcnt(0)
	v_add_f32_e32 v0, v0, v24
	ds_bpermute_b32 v24, v15, v0
	s_waitcnt lgkmcnt(0)
	v_add_f32_e32 v0, v0, v24
	ds_bpermute_b32 v24, v16, v0
	s_waitcnt lgkmcnt(0)
	v_add_f32_e32 v0, v0, v24
	ds_bpermute_b32 v24, v17, v0
	s_waitcnt lgkmcnt(0)
	v_add_f32_e32 v0, v0, v24
	v_fmamk_f32 v0, v0, 0x3b000000, v244
	v_cmp_gt_f32_e32 vcc, s83, v0
	v_mul_f32_e32 v24, 0x4f800000, v0
	s_nop 0
	v_cndmask_b32_e32 v0, v0, v24, vcc
	v_sqrt_f32_e32 v24, v0
	s_nop 0
	v_add_u32_e32 v25, -1, v24
	v_fma_f32 v26, -v25, v24, v0
	v_cmp_ge_f32_e64 s[2:3], 0, v26
	v_add_u32_e32 v26, 1, v24
	s_nop 0
	v_cndmask_b32_e64 v25, v24, v25, s[2:3]
	v_fma_f32 v24, -v26, v24, v0
	v_cmp_lt_f32_e64 s[2:3], 0, v24
	s_nop 1
	v_cndmask_b32_e64 v24, v25, v26, s[2:3]
	v_mul_f32_e32 v25, 0x37800000, v24
	v_cndmask_b32_e32 v24, v24, v25, vcc
	v_cmp_class_f32_e32 vcc, v0, v245
	s_nop 1
	v_cndmask_b32_e32 v0, v24, v0, vcc
	v_div_scale_f32 v24, s[2:3], v0, v0, 1.0
	v_rcp_f32_e32 v25, v24
	s_nop 0
	v_fma_f32 v26, -v24, v25, 1.0
	v_fmac_f32_e32 v25, v26, v25
	v_div_scale_f32 v26, vcc, 1.0, v0, 1.0
	v_mul_f32_e32 v27, v26, v25
	v_fma_f32 v28, -v24, v27, v26
	v_fmac_f32_e32 v27, v28, v25
	v_fma_f32 v24, -v24, v27, v26
	v_div_fmas_f32 v24, v24, v25, v27
	v_div_fixup_f32 v0, v24, v0, 1.0
	v_lshlrev_b32_e32 v24, 16, v92
	v_and_b32_e32 v25, 0xffff0000, v92
	v_lshlrev_b32_e32 v92, 16, v93
	v_and_b32_e32 v93, 0xffff0000, v93
	v_pk_mul_f32 v[88:89], v[88:89], v[0:1] op_sel_hi:[1,0]
	v_lshlrev_b32_e32 v26, 16, v94
	v_pk_mul_f32 v[92:93], v[88:89], v[92:93]
	v_mov_b32_e32 v88, v22
	v_mov_b32_e32 v89, v90
	v_mov_b32_e32 v90, v23
	v_and_b32_e32 v27, 0xffff0000, v94
	v_lshlrev_b32_e32 v94, 16, v95
	v_and_b32_e32 v95, 0xffff0000, v95
	v_pk_mul_f32 v[88:89], v[0:1], v[88:89] op_sel_hi:[0,1]
	v_pk_mul_f32 v[90:91], v[0:1], v[90:91] op_sel_hi:[0,1]
	v_pk_mul_f32 v[2:3], v[2:3], v[0:1] op_sel_hi:[1,0]
	v_pk_mul_f32 v[94:95], v[90:91], v[94:95]
	v_pk_mul_f32 v[90:91], v[88:89], v[26:27]
	v_pk_mul_f32 v[2:3], v[2:3], v[24:25]
	s_nop 0
	v_cvt_pk_bf16_f32 v88, v2, v3
	v_cvt_pk_bf16_f32 v89, v92, v93
	v_cvt_pk_bf16_f32 v90, v90, v91
	v_cvt_pk_bf16_f32 v91, v94, v95
	global_store_dwordx4 v[6:7], v[32:35], off
	global_store_dwordx4 v[6:7], v[40:43], off offset:1024
	global_store_dwordx4 v[6:7], v[48:51], off offset:2048
	global_store_dwordx4 v[6:7], v[56:59], off offset:3072
	global_store_dwordx4 v[164:165], v[64:67], off
	global_store_dwordx4 v[164:165], v[72:75], off offset:1024
	global_store_dwordx4 v[164:165], v[80:83], off offset:2048
	global_store_dwordx4 v[164:165], v[88:91], off offset:3072
	v_lshl_add_u64 v[6:7], v[6:7], 0, s[6:7]
	s_add_i32 s10, s10, s4
	s_cmpk_lt_i32 s10, 0x2400
	s_cbranch_scc1 .LBB0_769

; __device__ __forceinline__ float shx(float v, int mask, int lane) { return __int_as_float(__builtin_amdgcn_ds_bpermute((lane ^ mask) << 2, __float_as_int(v))); }
; __device__ __forceinline__ void attn_dif_unit(LAS unsigned char* lds, const int tid, const int wave_s, const bf16_t* q, const bf16_t* k0, const bf16_t* k1, const bf16_t* vt0, const bf16_t* vt1, ...
;     ...
;     const float inv0 = 1.f / (l_run[0] + shx(l_run[0], 32, lane)), inv1 = lamf / (l_run[1] + shx(l_run[1], 32, lane));
;     float ss = 0.f;
; #pragma unroll
;     for (int i = 0; i < 4; ++i)
; #pragma unroll
;         for (int r = 0; r < 16; ++r) { const float v = oacc[0][i][r] * inv0 - oacc[1][i][r] * inv1; oacc[0][i][r] = v; ss += v * v; }
.LBB0_980:
	ds_bpermute_b32 v0, v203, v219
	s_lshl_b64 s[2:3], s[2:3], 1
	s_add_u32 s2, s33, s2
	s_addc_u32 s3, s36, s3
	s_lshl_b32 s6, s42, 1
	s_add_u32 s6, s2, s6
	s_waitcnt lgkmcnt(0)
	v_add_f32_e32 v0, v219, v0
	s_addc_u32 s7, s3, 0
	v_div_scale_f32 v2, s[2:3], v0, v0, 1.0
	v_rcp_f32_e32 v3, v2
	s_mov_b32 s10, 0x3f24fd5c
	s_add_i32 s17, s17, s16
	s_cmpk_lt_i32 s17, 0x240
	v_fma_f32 v4, -v2, v3, 1.0
	v_fmac_f32_e32 v3, v4, v3
	v_div_scale_f32 v4, vcc, 1.0, v0, 1.0
	v_mul_f32_e32 v5, v4, v3
	v_fma_f32 v6, -v2, v5, v4
	v_fmac_f32_e32 v5, v6, v3
	v_fma_f32 v2, -v2, v5, v4
	v_div_fmas_f32 v2, v2, v3, v5
	v_div_fixup_f32 v0, v2, v0, 1.0
	ds_bpermute_b32 v2, v203, v216
	s_waitcnt lgkmcnt(0)
	v_add_f32_e32 v2, v216, v2
	v_div_scale_f32 v3, s[2:3], v2, v2, v253
	v_rcp_f32_e32 v4, v3
	s_nop 0
	v_fma_f32 v5, -v3, v4, 1.0
	v_fmac_f32_e32 v4, v5, v4
	v_div_scale_f32 v5, vcc, v253, v2, v253
	v_mul_f32_e32 v6, v5, v4
	v_fma_f32 v7, -v3, v6, v5
	v_fmac_f32_e32 v6, v7, v4
	v_fma_f32 v3, -v3, v6, v5
	v_div_fmas_f32 v3, v3, v4, v6
	v_div_fixup_f32 v2, v3, v2, v253
	v_pk_mul_f32 v[6:7], v[114:115], v[2:3] op_sel_hi:[1,0]
	v_pk_mul_f32 v[4:5], v[112:113], v[2:3] op_sel_hi:[1,0]
	v_pk_fma_f32 v[146:147], v[130:131], v[0:1], v[6:7] op_sel_hi:[1,0,1] neg_lo:[0,0,1] neg_hi:[0,0,1]
	v_pk_mul_f32 v[6:7], v[116:117], v[2:3] op_sel_hi:[1,0]
	v_pk_fma_f32 v[144:145], v[128:129], v[0:1], v[4:5] op_sel_hi:[1,0,1] neg_lo:[0,0,1] neg_hi:[0,0,1]
	v_pk_fma_f32 v[128:129], v[132:133], v[0:1], v[6:7] op_sel_hi:[1,0,1] neg_lo:[0,0,1] neg_hi:[0,0,1]
	v_pk_mul_f32 v[6:7], v[118:119], v[2:3] op_sel_hi:[1,0]
	v_pk_mul_f32 v[4:5], v[144:145], v[144:145]
	v_pk_fma_f32 v[130:131], v[134:135], v[0:1], v[6:7] op_sel_hi:[1,0,1] neg_lo:[0,0,1] neg_hi:[0,0,1]
	v_pk_mul_f32 v[6:7], v[120:121], v[2:3] op_sel_hi:[1,0]
	v_pk_mul_f32 v[148:149], v[146:147], v[146:147]
	v_pk_fma_f32 v[118:119], v[136:137], v[0:1], v[6:7] op_sel_hi:[1,0,1] neg_lo:[0,0,1] neg_hi:[0,0,1]
	v_pk_mul_f32 v[6:7], v[122:123], v[2:3] op_sel_hi:[1,0]
	v_pk_mul_f32 v[132:133], v[128:129], v[128:129]
	v_pk_fma_f32 v[122:123], v[138:139], v[0:1], v[6:7] op_sel_hi:[1,0,1] neg_lo:[0,0,1] neg_hi:[0,0,1]
	v_pk_mul_f32 v[6:7], v[124:125], v[2:3] op_sel_hi:[1,0]
	v_pk_mul_f32 v[134:135], v[130:131], v[130:131]
	v_pk_fma_f32 v[114:115], v[140:141], v[0:1], v[6:7] op_sel_hi:[1,0,1] neg_lo:[0,0,1] neg_hi:[0,0,1]
	v_pk_mul_f32 v[6:7], v[126:127], v[2:3] op_sel_hi:[1,0]
	v_pk_mul_f32 v[136:137], v[118:119], v[118:119]
	v_pk_fma_f32 v[120:121], v[142:143], v[0:1], v[6:7] op_sel_hi:[1,0,1] neg_lo:[0,0,1] neg_hi:[0,0,1]
	v_pk_mul_f32 v[6:7], v[80:81], v[2:3] op_sel_hi:[1,0]
	v_pk_mul_f32 v[138:139], v[122:123], v[122:123]
	v_pk_fma_f32 v[112:113], v[96:97], v[0:1], v[6:7] op_sel_hi:[1,0,1] neg_lo:[0,0,1] neg_hi:[0,0,1]
	v_pk_mul_f32 v[6:7], v[82:83], v[2:3] op_sel_hi:[1,0]
	v_pk_mul_f32 v[124:125], v[114:115], v[114:115]
	v_pk_fma_f32 v[116:117], v[98:99], v[0:1], v[6:7] op_sel_hi:[1,0,1] neg_lo:[0,0,1] neg_hi:[0,0,1]
	v_pk_mul_f32 v[6:7], v[84:85], v[2:3] op_sel_hi:[1,0]
	v_pk_mul_f32 v[126:127], v[120:121], v[120:121]
	v_pk_fma_f32 v[96:97], v[100:101], v[0:1], v[6:7] op_sel_hi:[1,0,1] neg_lo:[0,0,1] neg_hi:[0,0,1]
	v_pk_mul_f32 v[6:7], v[86:87], v[2:3] op_sel_hi:[1,0]
	v_pk_mul_f32 v[140:141], v[112:113], v[112:113]
	v_pk_fma_f32 v[98:99], v[102:103], v[0:1], v[6:7] op_sel_hi:[1,0,1] neg_lo:[0,0,1] neg_hi:[0,0,1]
	v_pk_mul_f32 v[6:7], v[88:89], v[2:3] op_sel_hi:[1,0]
	v_pk_mul_f32 v[142:143], v[116:117], v[116:117]
	v_pk_fma_f32 v[84:85], v[104:105], v[0:1], v[6:7] op_sel_hi:[1,0,1] neg_lo:[0,0,1] neg_hi:[0,0,1]
	v_pk_mul_f32 v[6:7], v[90:91], v[2:3] op_sel_hi:[1,0]
	v_pk_mul_f32 v[100:101], v[96:97], v[96:97]
	v_pk_fma_f32 v[88:89], v[106:107], v[0:1], v[6:7] op_sel_hi:[1,0,1] neg_lo:[0,0,1] neg_hi:[0,0,1]
	v_pk_mul_f32 v[6:7], v[92:93], v[2:3] op_sel_hi:[1,0]
	v_pk_mul_f32 v[102:103], v[98:99], v[98:99]
	v_pk_fma_f32 v[80:81], v[108:109], v[0:1], v[6:7] op_sel_hi:[1,0,1] neg_lo:[0,0,1] neg_hi:[0,0,1]
	v_pk_mul_f32 v[6:7], v[94:95], v[2:3] op_sel_hi:[1,0]
	v_pk_mul_f32 v[104:105], v[84:85], v[84:85]
	v_pk_fma_f32 v[86:87], v[110:111], v[0:1], v[6:7] op_sel_hi:[1,0,1] neg_lo:[0,0,1] neg_hi:[0,0,1]
	v_pk_mul_f32 v[6:7], v[48:49], v[2:3] op_sel_hi:[1,0]
	v_pk_mul_f32 v[90:91], v[88:89], v[88:89]
	v_pk_fma_f32 v[64:65], v[64:65], v[0:1], v[6:7] op_sel_hi:[1,0,1] neg_lo:[0,0,1] neg_hi:[0,0,1]
	v_pk_mul_f32 v[6:7], v[50:51], v[2:3] op_sel_hi:[1,0]
	v_pk_mul_f32 v[92:93], v[80:81], v[80:81]
	v_pk_fma_f32 v[82:83], v[66:67], v[0:1], v[6:7] op_sel_hi:[1,0,1] neg_lo:[0,0,1] neg_hi:[0,0,1]
	v_pk_mul_f32 v[6:7], v[52:53], v[2:3] op_sel_hi:[1,0]
	v_pk_mul_f32 v[94:95], v[86:87], v[86:87]
	v_pk_fma_f32 v[52:53], v[68:69], v[0:1], v[6:7] op_sel_hi:[1,0,1] neg_lo:[0,0,1] neg_hi:[0,0,1]
	v_pk_mul_f32 v[6:7], v[54:55], v[2:3] op_sel_hi:[1,0]
	v_pk_mul_f32 v[106:107], v[64:65], v[64:65]
	v_pk_fma_f32 v[66:67], v[70:71], v[0:1], v[6:7] op_sel_hi:[1,0,1] neg_lo:[0,0,1] neg_hi:[0,0,1]
	v_pk_mul_f32 v[6:7], v[56:57], v[2:3] op_sel_hi:[1,0]
	v_pk_mul_f32 v[108:109], v[82:83], v[82:83]
	v_pk_fma_f32 v[50:51], v[72:73], v[0:1], v[6:7] op_sel_hi:[1,0,1] neg_lo:[0,0,1] neg_hi:[0,0,1]
	v_pk_mul_f32 v[6:7], v[58:59], v[2:3] op_sel_hi:[1,0]
	v_pk_mul_f32 v[68:69], v[52:53], v[52:53]
	v_pk_fma_f32 v[56:57], v[74:75], v[0:1], v[6:7] op_sel_hi:[1,0,1] neg_lo:[0,0,1] neg_hi:[0,0,1]
	v_pk_mul_f32 v[6:7], v[60:61], v[2:3] op_sel_hi:[1,0]
	v_pk_mul_f32 v[70:71], v[66:67], v[66:67]
	v_pk_fma_f32 v[48:49], v[76:77], v[0:1], v[6:7] op_sel_hi:[1,0,1] neg_lo:[0,0,1] neg_hi:[0,0,1]
	v_pk_mul_f32 v[6:7], v[62:63], v[2:3] op_sel_hi:[1,0]
	v_pk_mul_f32 v[72:73], v[50:51], v[50:51]
; __device__ __forceinline__ float shx(float v, int mask, int lane) { return __int_as_float(__builtin_amdgcn_ds_bpermute((lane ^ mask) << 2, __float_as_int(v))); }
; __device__ __forceinline__ void attn_dif_unit(LAS unsigned char* lds, const int tid, const int wave_s, const bf16_t* q, const bf16_t* k0, const bf16_t* k1, const bf16_t* vt0, const bf16_t* vt1, ...
;     ...
;         for (int r = 0; r < 16; ++r) { const float v = oacc[0][i][r] * inv0 - oacc[1][i][r] * inv1; oacc[0][i][r] = v; ss += v * v; }
;     ss += shx(ss, 32, lane);
;     const float rs = subscale / sqrtf(ss * (1.f / 128.f) + LN_EPS);
;     int c32b = c32, hib = hi, wb = w; asm volatile("" : "+v"(c32b), "+v"(hib), "+v"(wb));
;     const unsigned ob = (unsigned)((32 * wb + c32b) * D + 4 * hib) * 2u; const float* subp = sub + 4 * hib;
; #pragma unroll
;     for (int i = 0; i < 4; ++i)
; #pragma unroll
;         for (int g = 0; g < 4; ++g) { const int col = 32 * i + 8 * g; const f32x4 sb = *(const f32x4*)(subp + col);
	v_pk_fma_f32 v[54:55], v[78:79], v[0:1], v[6:7] op_sel_hi:[1,0,1] neg_lo:[0,0,1] neg_hi:[0,0,1]
	v_pk_mul_f32 v[6:7], v[16:17], v[2:3] op_sel_hi:[1,0]
	v_pk_mul_f32 v[58:59], v[56:57], v[56:57]
	v_pk_fma_f32 v[12:13], v[32:33], v[0:1], v[6:7] op_sel_hi:[1,0,1] neg_lo:[0,0,1] neg_hi:[0,0,1]
	v_pk_mul_f32 v[6:7], v[18:19], v[2:3] op_sel_hi:[1,0]
	v_pk_mul_f32 v[60:61], v[48:49], v[48:49]
	v_pk_fma_f32 v[32:33], v[34:35], v[0:1], v[6:7] op_sel_hi:[1,0,1] neg_lo:[0,0,1] neg_hi:[0,0,1]
	v_pk_mul_f32 v[6:7], v[20:21], v[2:3] op_sel_hi:[1,0]
	v_pk_mul_f32 v[62:63], v[54:55], v[54:55]
	v_pk_fma_f32 v[10:11], v[36:37], v[0:1], v[6:7] op_sel_hi:[1,0,1] neg_lo:[0,0,1] neg_hi:[0,0,1]
	v_pk_mul_f32 v[6:7], v[22:23], v[2:3] op_sel_hi:[1,0]
	v_pk_mul_f32 v[74:75], v[12:13], v[12:13]
	v_pk_fma_f32 v[18:19], v[38:39], v[0:1], v[6:7] op_sel_hi:[1,0,1] neg_lo:[0,0,1] neg_hi:[0,0,1]
	v_pk_mul_f32 v[6:7], v[24:25], v[2:3] op_sel_hi:[1,0]
	v_pk_mul_f32 v[34:35], v[32:33], v[32:33]
	v_pk_fma_f32 v[8:9], v[40:41], v[0:1], v[6:7] op_sel_hi:[1,0,1] neg_lo:[0,0,1] neg_hi:[0,0,1]
	v_pk_mul_f32 v[6:7], v[26:27], v[2:3] op_sel_hi:[1,0]
	v_pk_mul_f32 v[20:21], v[10:11], v[10:11]
	v_pk_fma_f32 v[16:17], v[42:43], v[0:1], v[6:7] op_sel_hi:[1,0,1] neg_lo:[0,0,1] neg_hi:[0,0,1]
	v_pk_mul_f32 v[6:7], v[28:29], v[2:3] op_sel_hi:[1,0]
	v_pk_mul_f32 v[2:3], v[30:31], v[2:3] op_sel_hi:[1,0]
	v_pk_fma_f32 v[6:7], v[44:45], v[0:1], v[6:7] op_sel_hi:[1,0,1] neg_lo:[0,0,1] neg_hi:[0,0,1]
	v_pk_fma_f32 v[14:15], v[46:47], v[0:1], v[2:3] op_sel_hi:[1,0,1] neg_lo:[0,0,1] neg_hi:[0,0,1]
	v_add_f32_e32 v0, v4, v5
	v_add_f32_e32 v0, v148, v0
	v_add_f32_e32 v0, v149, v0
	v_add_f32_e32 v0, v132, v0
	v_add_f32_e32 v0, v133, v0
	v_add_f32_e32 v0, v134, v0
	v_add_f32_e32 v0, v135, v0
	v_add_f32_e32 v0, v136, v0
	v_add_f32_e32 v0, v137, v0
	v_add_f32_e32 v0, v138, v0
	v_add_f32_e32 v0, v139, v0
	v_add_f32_e32 v0, v124, v0
	v_add_f32_e32 v0, v125, v0
	v_add_f32_e32 v0, v126, v0
	v_add_f32_e32 v0, v127, v0
	v_add_f32_e32 v0, v140, v0
	v_add_f32_e32 v0, v141, v0
	v_add_f32_e32 v0, v142, v0
	v_add_f32_e32 v0, v143, v0
	v_add_f32_e32 v0, v100, v0
	v_add_f32_e32 v0, v101, v0
	v_add_f32_e32 v0, v102, v0
	v_add_f32_e32 v0, v103, v0
	v_add_f32_e32 v0, v104, v0
	v_add_f32_e32 v0, v105, v0
	v_add_f32_e32 v0, v90, v0
	v_add_f32_e32 v0, v91, v0
	v_add_f32_e32 v0, v92, v0
	v_add_f32_e32 v0, v93, v0
	v_add_f32_e32 v0, v94, v0
	v_add_f32_e32 v0, v95, v0
	v_add_f32_e32 v0, v106, v0
	v_add_f32_e32 v0, v107, v0
	v_add_f32_e32 v0, v108, v0
	v_add_f32_e32 v0, v109, v0
	v_add_f32_e32 v0, v68, v0
	v_add_f32_e32 v0, v69, v0
	v_add_f32_e32 v0, v70, v0
	v_add_f32_e32 v0, v71, v0
	v_add_f32_e32 v0, v72, v0
	v_add_f32_e32 v0, v73, v0
	v_add_f32_e32 v0, v58, v0
	v_add_f32_e32 v0, v59, v0
	v_add_f32_e32 v0, v60, v0
	v_add_f32_e32 v0, v61, v0
	v_add_f32_e32 v0, v62, v0
	v_add_f32_e32 v0, v63, v0
	v_add_f32_e32 v0, v74, v0
	v_add_f32_e32 v0, v75, v0
	v_add_f32_e32 v0, v34, v0
	v_add_f32_e32 v0, v35, v0
	v_add_f32_e32 v0, v20, v0
	v_pk_mul_f32 v[22:23], v[18:19], v[18:19]
	v_add_f32_e32 v0, v21, v0
	v_add_f32_e32 v0, v22, v0
	v_pk_mul_f32 v[24:25], v[8:9], v[8:9]
	v_add_f32_e32 v0, v23, v0
	v_add_f32_e32 v0, v24, v0
	v_pk_mul_f32 v[26:27], v[16:17], v[16:17]
	v_add_f32_e32 v0, v25, v0
	v_add_f32_e32 v0, v26, v0
	v_pk_mul_f32 v[28:29], v[6:7], v[6:7]
	v_add_f32_e32 v0, v27, v0
	v_add_f32_e32 v0, v28, v0
	v_pk_mul_f32 v[2:3], v[14:15], v[14:15]
	v_add_f32_e32 v0, v29, v0
	v_add_f32_e32 v0, v2, v0
	v_add_f32_e32 v0, v3, v0
	ds_bpermute_b32 v2, v203, v0
	s_waitcnt lgkmcnt(0)
	v_add_f32_e32 v0, v0, v2
	v_fmamk_f32 v0, v0, 0x3c000000, v244
	v_cmp_gt_f32_e32 vcc, s83, v0
	v_mul_f32_e32 v2, 0x4f800000, v0
	s_nop 0
	v_cndmask_b32_e32 v0, v0, v2, vcc
	v_sqrt_f32_e32 v2, v0
	s_nop 0
	v_add_u32_e32 v3, -1, v2
	v_fma_f32 v4, -v3, v2, v0
	v_cmp_ge_f32_e64 s[2:3], 0, v4
	v_add_u32_e32 v4, 1, v2
	s_nop 0
	v_cndmask_b32_e64 v3, v2, v3, s[2:3]
	v_fma_f32 v2, -v4, v2, v0
	v_cmp_lt_f32_e64 s[2:3], 0, v2
	s_nop 1
	v_cndmask_b32_e64 v2, v3, v4, s[2:3]
	v_mul_f32_e32 v3, 0x37800000, v2
	v_cndmask_b32_e32 v2, v2, v3, vcc
	v_cmp_class_f32_e32 vcc, v0, v245
	s_nop 1
	v_cndmask_b32_e32 v0, v2, v0, vcc
	v_div_scale_f32 v2, s[2:3], v0, v0, s10
	v_rcp_f32_e32 v3, v2
	s_nop 0
	v_fma_f32 v4, -v2, v3, 1.0
	v_fmac_f32_e32 v3, v4, v3
	v_div_scale_f32 v4, vcc, s10, v0, s10
	v_mul_f32_e32 v5, v4, v3
	v_fma_f32 v20, -v2, v5, v4
	v_fmac_f32_e32 v5, v20, v3
	v_fma_f32 v2, -v2, v5, v4
	v_div_fmas_f32 v2, v2, v3, v5
	v_div_fixup_f32 v0, v2, v0, s10
	v_mov_b32_e32 v2, v254
	v_lshrrev_b32_e32 v3, 5, v202
	v_mov_b32_e32 v4, v208
	v_pk_mul_f32 v[24:25], v[144:145], v[0:1] op_sel_hi:[1,0]
	v_lshlrev_b32_e32 v4, 11, v4
	v_lshl_add_u32 v4, v2, 16, v4
	v_lshlrev_b32_e32 v2, 2, v3
	v_ashrrev_i32_e32 v3, 31, v2
	v_lshl_add_u64 v[20:21], v[2:3], 2, s[4:5]
	v_add_lshl_u32 v22, v4, v2, 1
	global_load_dwordx4 v[28:31], v[20:21], off
	global_load_dwordx4 v[36:39], v[20:21], off offset:32
	global_load_dwordx4 v[40:43], v[20:21], off offset:64
	global_load_dwordx4 v[44:47], v[20:21], off offset:96
	global_load_dwordx4 v[60:63], v[20:21], off offset:128
	global_load_dwordx4 v[68:71], v[20:21], off offset:160
	global_load_dwordx4 v[72:75], v[20:21], off offset:192
	global_load_dwordx4 v[76:79], v[20:21], off offset:224
	global_load_dwordx4 v[92:95], v[20:21], off offset:256
	global_load_dwordx4 v[100:103], v[20:21], off offset:288
	global_load_dwordx4 v[104:107], v[20:21], off offset:320
	global_load_dwordx4 v[108:111], v[20:21], off offset:352
	global_load_dwordx4 v[124:127], v[20:21], off offset:384
	global_load_dwordx4 v[132:135], v[20:21], off offset:416
	global_load_dwordx4 v[136:139], v[20:21], off offset:448
	global_load_dwordx4 v[140:143], v[20:21], off offset:480
	v_pk_mul_f32 v[26:27], v[146:147], v[0:1] op_sel_hi:[1,0]
	v_pk_mul_f32 v[12:13], v[12:13], v[0:1] op_sel_hi:[1,0]
	v_pk_mul_f32 v[10:11], v[10:11], v[0:1] op_sel_hi:[1,0]
	v_pk_mul_f32 v[8:9], v[8:9], v[0:1] op_sel_hi:[1,0]
	v_pk_mul_f32 v[6:7], v[6:7], v[0:1] op_sel_hi:[1,0]
	s_waitcnt vmcnt(0)
; __device__ __forceinline__ u32x2 pk4(f32x4 v) { u32x2 w; w.x = cvt_pk_bf16(v[0], v[1]); w.y = cvt_pk_bf16(v[2], v[3]); return w; }
; __device__ __forceinline__ void attn_dif_unit(LAS unsigned char* lds, const int tid, const int wave_s, const bf16_t* q, const bf16_t* k0, const bf16_t* k1, const bf16_t* vt0, const bf16_t* vt1, ...
;     ...
;         for (int g = 0; g < 4; ++g) { const int col = 32 * i + 8 * g; const f32x4 sb = *(const f32x4*)(subp + col);
;             const f32x4 v = (f32x4){oacc[0][i][4 * g], oacc[0][i][4 * g + 1], oacc[0][i][4 * g + 2], oacc[0][i][4 * g + 3]} * rs * sb; *(u32x2*)((char*)o + ob + col * 2) = pk4(v); }
;     asm volatile("s_waitcnt lgkmcnt(0)" ::: "memory"); __builtin_amdgcn_s_barrier(); asm volatile("" ::: "memory");
	v_pk_mul_f32 v[2:3], v[28:29], v[24:25]
	v_pk_mul_f32 v[4:5], v[30:31], v[26:27]
	v_cvt_pk_bf16_f32 v2, v2, v3
	v_pk_mul_f32 v[24:25], v[128:129], v[0:1] op_sel_hi:[1,0]
	v_cvt_pk_bf16_f32 v3, v4, v5
	global_store_dwordx2 v22, v[2:3], s[6:7]
	v_pk_mul_f32 v[26:27], v[130:131], v[0:1] op_sel_hi:[1,0]
	v_pk_mul_f32 v[2:3], v[36:37], v[24:25]
	v_pk_mul_f32 v[4:5], v[38:39], v[26:27]
	v_cvt_pk_bf16_f32 v2, v2, v3
	v_pk_mul_f32 v[24:25], v[118:119], v[0:1] op_sel_hi:[1,0]
	v_cvt_pk_bf16_f32 v3, v4, v5
	global_store_dwordx2 v22, v[2:3], s[6:7] offset:16
	v_pk_mul_f32 v[26:27], v[122:123], v[0:1] op_sel_hi:[1,0]
	v_pk_mul_f32 v[2:3], v[40:41], v[24:25]
	v_pk_mul_f32 v[4:5], v[42:43], v[26:27]
	v_cvt_pk_bf16_f32 v2, v2, v3
	v_pk_mul_f32 v[24:25], v[114:115], v[0:1] op_sel_hi:[1,0]
	v_cvt_pk_bf16_f32 v3, v4, v5
	global_store_dwordx2 v22, v[2:3], s[6:7] offset:32
	v_pk_mul_f32 v[26:27], v[120:121], v[0:1] op_sel_hi:[1,0]
	v_pk_mul_f32 v[2:3], v[44:45], v[24:25]
	v_pk_mul_f32 v[4:5], v[46:47], v[26:27]
	v_cvt_pk_bf16_f32 v2, v2, v3
	v_pk_mul_f32 v[24:25], v[112:113], v[0:1] op_sel_hi:[1,0]
	v_cvt_pk_bf16_f32 v3, v4, v5
	global_store_dwordx2 v22, v[2:3], s[6:7] offset:48
	v_pk_mul_f32 v[26:27], v[116:117], v[0:1] op_sel_hi:[1,0]
	v_pk_mul_f32 v[2:3], v[60:61], v[24:25]
	v_pk_mul_f32 v[4:5], v[62:63], v[26:27]
	v_cvt_pk_bf16_f32 v2, v2, v3
	v_pk_mul_f32 v[24:25], v[96:97], v[0:1] op_sel_hi:[1,0]
	v_cvt_pk_bf16_f32 v3, v4, v5
	global_store_dwordx2 v22, v[2:3], s[6:7] offset:64
	v_pk_mul_f32 v[26:27], v[98:99], v[0:1] op_sel_hi:[1,0]
	v_pk_mul_f32 v[2:3], v[68:69], v[24:25]
	v_pk_mul_f32 v[4:5], v[70:71], v[26:27]
	v_cvt_pk_bf16_f32 v2, v2, v3
	v_pk_mul_f32 v[24:25], v[84:85], v[0:1] op_sel_hi:[1,0]
	v_cvt_pk_bf16_f32 v3, v4, v5
	global_store_dwordx2 v22, v[2:3], s[6:7] offset:80
	v_pk_mul_f32 v[26:27], v[88:89], v[0:1] op_sel_hi:[1,0]
	v_pk_mul_f32 v[2:3], v[72:73], v[24:25]
	v_pk_mul_f32 v[4:5], v[74:75], v[26:27]
	v_cvt_pk_bf16_f32 v2, v2, v3
	v_pk_mul_f32 v[24:25], v[80:81], v[0:1] op_sel_hi:[1,0]
	v_cvt_pk_bf16_f32 v3, v4, v5
	global_store_dwordx2 v22, v[2:3], s[6:7] offset:96
	v_pk_mul_f32 v[26:27], v[86:87], v[0:1] op_sel_hi:[1,0]
	v_pk_mul_f32 v[2:3], v[76:77], v[24:25]
	v_pk_mul_f32 v[4:5], v[78:79], v[26:27]
	v_cvt_pk_bf16_f32 v2, v2, v3
	v_pk_mul_f32 v[24:25], v[64:65], v[0:1] op_sel_hi:[1,0]
	v_cvt_pk_bf16_f32 v3, v4, v5
	global_store_dwordx2 v22, v[2:3], s[6:7] offset:112
	v_pk_mul_f32 v[26:27], v[82:83], v[0:1] op_sel_hi:[1,0]
	v_pk_mul_f32 v[2:3], v[92:93], v[24:25]
	v_pk_mul_f32 v[4:5], v[94:95], v[26:27]
	v_cvt_pk_bf16_f32 v2, v2, v3
	v_pk_mul_f32 v[24:25], v[52:53], v[0:1] op_sel_hi:[1,0]
	v_cvt_pk_bf16_f32 v3, v4, v5
	global_store_dwordx2 v22, v[2:3], s[6:7] offset:128
	v_pk_mul_f32 v[26:27], v[66:67], v[0:1] op_sel_hi:[1,0]
	v_pk_mul_f32 v[2:3], v[100:101], v[24:25]
	v_pk_mul_f32 v[4:5], v[102:103], v[26:27]
	v_cvt_pk_bf16_f32 v2, v2, v3
	v_pk_mul_f32 v[24:25], v[50:51], v[0:1] op_sel_hi:[1,0]
	v_cvt_pk_bf16_f32 v3, v4, v5
	global_store_dwordx2 v22, v[2:3], s[6:7] offset:144
	v_pk_mul_f32 v[26:27], v[56:57], v[0:1] op_sel_hi:[1,0]
	v_pk_mul_f32 v[2:3], v[104:105], v[24:25]
	v_pk_mul_f32 v[4:5], v[106:107], v[26:27]
	v_cvt_pk_bf16_f32 v2, v2, v3
	v_pk_mul_f32 v[24:25], v[48:49], v[0:1] op_sel_hi:[1,0]
	v_cvt_pk_bf16_f32 v3, v4, v5
	global_store_dwordx2 v22, v[2:3], s[6:7] offset:160
	v_pk_mul_f32 v[26:27], v[54:55], v[0:1] op_sel_hi:[1,0]
	v_pk_mul_f32 v[2:3], v[108:109], v[24:25]
	v_pk_mul_f32 v[4:5], v[110:111], v[26:27]
	v_cvt_pk_bf16_f32 v2, v2, v3
	v_pk_mul_f32 v[24:25], v[32:33], v[0:1] op_sel_hi:[1,0]
	v_cvt_pk_bf16_f32 v3, v4, v5
	global_store_dwordx2 v22, v[2:3], s[6:7] offset:176
	v_pk_mul_f32 v[2:3], v[124:125], v[12:13]
	v_pk_mul_f32 v[4:5], v[126:127], v[24:25]
	v_cvt_pk_bf16_f32 v2, v2, v3
	v_pk_mul_f32 v[12:13], v[18:19], v[0:1] op_sel_hi:[1,0]
	v_cvt_pk_bf16_f32 v3, v4, v5
	global_store_dwordx2 v22, v[2:3], s[6:7] offset:192
	v_pk_mul_f32 v[2:3], v[132:133], v[10:11]
	v_pk_mul_f32 v[4:5], v[134:135], v[12:13]
	v_cvt_pk_bf16_f32 v2, v2, v3
	v_pk_mul_f32 v[10:11], v[16:17], v[0:1] op_sel_hi:[1,0]
	v_cvt_pk_bf16_f32 v3, v4, v5
	global_store_dwordx2 v22, v[2:3], s[6:7] offset:208
	v_pk_mul_f32 v[2:3], v[136:137], v[8:9]
	v_pk_mul_f32 v[4:5], v[138:139], v[10:11]
	v_cvt_pk_bf16_f32 v2, v2, v3
	v_pk_mul_f32 v[8:9], v[14:15], v[0:1] op_sel_hi:[1,0]
	v_cvt_pk_bf16_f32 v3, v4, v5
	global_store_dwordx2 v22, v[2:3], s[6:7] offset:224
	v_pk_mul_f32 v[2:3], v[140:141], v[6:7]
	v_pk_mul_f32 v[4:5], v[142:143], v[8:9]
	v_cvt_pk_bf16_f32 v2, v2, v3
	s_nop 0
	v_cvt_pk_bf16_f32 v3, v4, v5
	global_store_dwordx2 v22, v[2:3], s[6:7] offset:240
	s_waitcnt lgkmcnt(0)
	s_barrier
	s_cbranch_scc0 .LBB0_1007
